# attention QK: conflict-free K swizzle (row&15) + 4-deep K fragment prefetch ring, both groups (on top of v046)
# speedup vs baseline: 1.0112x; 1.0062x over previous
.LBB0_509:
	s_xor_b64 s[18:19], s[4:5], -1
	s_lshl_b64 s[4:5], s[0:1], 1
	s_add_u32 s22, s56, s4
	s_addc_u32 s23, s57, s5
	v_mov_b32_e32 v2, v208
	s_add_u32 s0, s58, s4
	s_addc_u32 s1, s59, s5
	v_readfirstlane_b32 s20, v2
	s_ashr_i32 s24, s20, 6
	s_and_b32 s20, s20, 0x3fffffc0
	s_lshl_b32 s20, s20, 2
	v_and_b32_e32 v219, 31, v2
	s_add_i32 s21, s20, 0
	s_lshl_b32 s20, s24, 5
	v_or_b32_e32 v0, s20, v219
	s_waitcnt lgkmcnt(0)
	v_ashrrev_i32_e32 v1, 31, v0
	v_bfe_u32 v218, v2, 5, 1
	v_lshlrev_b64 v[0:1], 11, v[0:1]
	v_lshl_add_u64 v[0:1], s[22:23], 0, v[0:1]
	v_lshlrev_b32_e32 v210, 4, v218
	v_lshl_add_u64 v[0:1], v[0:1], 0, v[210:211]
	global_load_dwordx4 v[160:163], v[0:1], off
	global_load_dwordx4 v[164:167], v[0:1], off offset:32
	global_load_dwordx4 v[168:171], v[0:1], off offset:64
	global_load_dwordx4 v[172:175], v[0:1], off offset:96
	global_load_dwordx4 v[176:179], v[0:1], off offset:128
	global_load_dwordx4 v[180:183], v[0:1], off offset:160
	global_load_dwordx4 v[184:187], v[0:1], off offset:192
	global_load_dwordx4 v[188:191], v[0:1], off offset:224
	s_lshl_b32 s22, s24, 3
	v_bfe_u32 v1, v2, 4, 2
	v_or_b32_e32 v0, s22, v1
	v_bitop3_b32 v4, v1, v2, 15 bitop3:0x78
	v_ashrrev_i32_e32 v1, 31, v0
	v_lshlrev_b64 v[212:213], 10, v[0:1]
	v_or_b32_e32 v0, 4, v0
	v_and_b32_e32 v3, 15, v2
	v_ashrrev_i32_e32 v1, 31, v0
	v_bitop3_b32 v3, v0, v3, 7 bitop3:0x6c
	s_and_b32 s25, s24, 1
	s_lshl_b32 s25, s25, 3
	v_xor_b32_e32 v4, s25, v4
	v_xor_b32_e32 v3, s25, v3
	v_lshlrev_b64 v[214:215], 10, v[0:1]
	v_bfe_u32 v0, v2, 2, 3
	v_bitop3_b32 v0, s22, -13, v0 bitop3:0xc8
	v_lshrrev_b32_e32 v1, 2, v2
	s_lshl_b32 s22, s24, 3
	v_and_b32_e32 v1, 4, v1
	s_and_b32 s22, s22, 8
	v_or3_b32 v0, v0, v1, s22
	s_add_i32 s21, s21, 0x24000
	v_ashrrev_i32_e32 v1, 31, v0
	v_lshlrev_b32_e32 v11, 3, v2
	s_lshl_b32 s22, s24, 11
	v_lshl_or_b32 v212, v4, 3, v212
	v_lshlrev_b64 v[216:217], 10, v[0:1]
	v_and_b32_e32 v0, 32, v2
	v_and_b32_e32 v1, 24, v11
	s_cmp_lg_u32 0, -1
	v_or3_b32 v216, v216, v1, v0
	v_lshlrev_b64 v[0:1], 1, v[212:213]
	s_cselect_b32 s23, 0, 0
	v_and_b32_e32 v10, 63, v2
	v_lshl_or_b32 v214, v3, 3, v214
	v_lshlrev_b32_e32 v12, 4, v2
	v_lshlrev_b32_e32 v13, 1, v2
	v_lshl_add_u64 v[2:3], s[0:1], 0, v[0:1]
	s_add_i32 s75, s22, s23
	s_mov_b32 s25, m0
	s_mov_b32 m0, s75
	s_nop 0
	global_load_lds_dwordx4 v[2:3], off
	s_mov_b32 m0, s25
	v_lshlrev_b64 v[2:3], 1, v[214:215]
	s_or_b32 s25, s22, 0x400
	v_lshl_add_u64 v[4:5], s[0:1], 0, v[2:3]
	s_add_i32 s77, s25, s23
	s_mov_b32 s84, m0
	s_mov_b32 m0, s77
	s_nop 0
	global_load_lds_dwordx4 v[4:5], off
	s_mov_b32 m0, s84
	s_lshl_b32 s24, s24, 12
	v_lshlrev_b64 v[4:5], 1, v[216:217]
	s_add_i32 s84, s23, 0xc000
	v_lshl_add_u64 v[6:7], s[14:15], 0, v[4:5]
	s_add_i32 s77, s24, s84
	s_mov_b32 s85, m0
	s_mov_b32 m0, s77
	s_nop 0
	global_load_lds_dwordx4 v[6:7], off
	s_mov_b32 m0, s85
	s_or_b32 s85, s24, 0x400
	s_add_i32 s86, s85, s84
	v_lshl_add_u64 v[8:9], v[6:7], 0, s[8:9]
	s_mov_b32 s87, m0
	s_mov_b32 m0, s86
	s_nop 0
	global_load_lds_dwordx4 v[8:9], off
	s_mov_b32 m0, s87
	s_or_b32 s86, s24, 0x800
	s_add_i32 s87, s86, s84
	v_lshl_add_u64 v[8:9], v[6:7], 0, s[10:11]
	s_mov_b32 s96, m0
	s_mov_b32 m0, s87
	s_nop 0
	global_load_lds_dwordx4 v[8:9], off
	s_mov_b32 m0, s96
	s_or_b32 s87, s24, 0xc00
	s_add_i32 s96, s87, s84
	s_add_u32 s0, s0, 0x20000
	v_lshl_add_u64 v[6:7], v[6:7], 0, s[12:13]
	s_mov_b32 s97, m0
	s_mov_b32 m0, s96
	s_nop 0
	global_load_lds_dwordx4 v[6:7], off
	s_mov_b32 m0, s97
	s_addc_u32 s1, s1, 0
	s_add_i32 s96, s23, 0x4000
	v_lshl_add_u64 v[0:1], s[0:1], 0, v[0:1]
	s_add_i32 s22, s22, s96
	s_mov_b32 s97, m0
	s_mov_b32 m0, s22
	s_nop 0
	global_load_lds_dwordx4 v[0:1], off
	s_mov_b32 m0, s97
	v_lshl_add_u64 v[0:1], s[0:1], 0, v[2:3]
	s_add_i32 s25, s25, s96
	s_mov_b32 s0, m0
	s_mov_b32 m0, s25
	s_nop 0
	global_load_lds_dwordx4 v[0:1], off
	s_mov_b32 m0, s0
	s_add_i32 s23, s23, 0x14000
	v_lshl_add_u64 v[0:1], s[16:17], 0, v[4:5]
	s_add_i32 s24, s24, s23
	s_mov_b32 s0, m0
	s_mov_b32 m0, s24
	s_nop 0
	global_load_lds_dwordx4 v[0:1], off
	s_mov_b32 m0, s0
	v_lshl_add_u64 v[2:3], v[0:1], 0, s[8:9]
	s_add_i32 s85, s85, s23
	s_mov_b32 s0, m0
	s_mov_b32 m0, s85
	s_nop 0
	global_load_lds_dwordx4 v[2:3], off
	s_mov_b32 m0, s0
	v_lshl_add_u64 v[2:3], v[0:1], 0, s[10:11]
	s_add_i32 s86, s86, s23
	s_mov_b32 s0, m0
	s_mov_b32 m0, s86
	s_nop 0
	global_load_lds_dwordx4 v[2:3], off
	s_mov_b32 m0, s0
	v_lshl_add_u64 v[0:1], v[0:1], 0, s[12:13]
	s_add_i32 s87, s87, s23
	s_mov_b32 s0, m0
	s_mov_b32 m0, s87
	s_nop 0
	global_load_lds_dwordx4 v[0:1], off
	s_mov_b32 m0, s0
	s_movk_i32 s0, 0x70
	v_and_b32_e32 v1, 0x70, v12
	v_bitop3_b32 v221, v210, v12, s0 bitop3:0x78
	s_movk_i32 s0, 0x60
	v_bitop3_b32 v224, v210, v1, s0 bitop3:0x36
	s_movk_i32 s0, 0x80
	v_and_b32_e32 v0, 0x118, v11
	v_bitop3_b32 v225, v210, v1, s0 bitop3:0x36
	s_movk_i32 s0, 0xa0
	v_and_b32_e32 v14, 0xc0, v12
	v_bitop3_b32 v227, v210, v1, s0 bitop3:0x36
	s_movk_i32 s0, 0xc0
	v_and_or_b32 v0, v13, 32, v0
	v_bitop3_b32 v228, v210, v1, s0 bitop3:0x36
	s_movk_i32 s0, 0xe0
	v_add3_u32 v230, v14, s84, v0
	v_mov_b32_e32 v14, v211
	v_mov_b32_e32 v15, v211
	v_bitop3_b32 v222, v210, v1, 32 bitop3:0x36
	v_bitop3_b32 v223, v210, v1, 64 bitop3:0x36
	v_bitop3_b32 v229, v210, v1, s0 bitop3:0x36
	v_and_b32_e32 v236, 0x80, v12
	v_xor_b32_e32 v221, v236, v221
	v_xor_b32_e32 v222, v236, v222
	v_xor_b32_e32 v223, v236, v223
	v_xor_b32_e32 v224, v236, v224
	v_xor_b32_e32 v225, v236, v225
	v_xor_b32_e32 v227, v236, v227
	v_xor_b32_e32 v228, v236, v228
	v_xor_b32_e32 v229, v236, v229
	v_cmp_gt_u32_e64 s[0:1], 32, v10
	s_add_u32 s84, s66, s4
	v_mov_b32_e32 v0, v211
	v_mov_b32_e32 v1, v211
	v_mov_b32_e32 v2, v211
	v_mov_b32_e32 v3, v211
	v_mov_b32_e32 v4, v211
	v_mov_b32_e32 v5, v211
	v_mov_b32_e32 v6, v211
	v_mov_b32_e32 v7, v211
	v_mov_b32_e32 v8, v211
	v_mov_b32_e32 v9, v211
	v_mov_b32_e32 v10, v211
	v_mov_b32_e32 v11, v211
	v_mov_b32_e32 v12, v211
	v_mov_b32_e32 v13, v211
	v_mov_b64_e32 v[126:127], v[14:15]
	v_mov_b64_e32 v[110:111], v[14:15]
	v_mov_b64_e32 v[94:95], v[14:15]
	v_mov_b64_e32 v[78:79], v[14:15]
	v_mov_b64_e32 v[62:63], v[14:15]
	v_mov_b64_e32 v[46:47], v[14:15]
	v_mov_b64_e32 v[30:31], v[14:15]
	s_mov_b32 s74, 2
	s_mov_b32 s76, 0
	v_lshlrev_b32_e32 v220, 8, v219
	v_lshl_add_u32 v226, v219, 2, s21
	s_addc_u32 s85, s67, s5
	v_mov_b32_e32 v232, 0
	v_mov_b32_e32 v231, 0xf149f2ca
	s_mov_b64 s[22:23], 0
	v_mov_b64_e32 v[124:125], v[12:13]
	v_mov_b64_e32 v[122:123], v[10:11]
	v_mov_b64_e32 v[120:121], v[8:9]
	v_mov_b64_e32 v[118:119], v[6:7]
	v_mov_b64_e32 v[116:117], v[4:5]
	v_mov_b64_e32 v[114:115], v[2:3]
	v_mov_b64_e32 v[112:113], v[0:1]
	v_mov_b64_e32 v[108:109], v[12:13]
	v_mov_b64_e32 v[106:107], v[10:11]
	v_mov_b64_e32 v[104:105], v[8:9]
	v_mov_b64_e32 v[102:103], v[6:7]
	v_mov_b64_e32 v[100:101], v[4:5]
	v_mov_b64_e32 v[98:99], v[2:3]
	v_mov_b64_e32 v[96:97], v[0:1]
	v_mov_b64_e32 v[92:93], v[12:13]
	v_mov_b64_e32 v[90:91], v[10:11]
	v_mov_b64_e32 v[88:89], v[8:9]
	v_mov_b64_e32 v[86:87], v[6:7]
	v_mov_b64_e32 v[84:85], v[4:5]
	v_mov_b64_e32 v[82:83], v[2:3]
	v_mov_b64_e32 v[80:81], v[0:1]
	v_mov_b64_e32 v[76:77], v[12:13]
	v_mov_b64_e32 v[74:75], v[10:11]
	v_mov_b64_e32 v[72:73], v[8:9]
	v_mov_b64_e32 v[70:71], v[6:7]
	v_mov_b64_e32 v[68:69], v[4:5]
	v_mov_b64_e32 v[66:67], v[2:3]
	v_mov_b64_e32 v[64:65], v[0:1]
	v_mov_b64_e32 v[60:61], v[12:13]
	v_mov_b64_e32 v[58:59], v[10:11]
	v_mov_b64_e32 v[56:57], v[8:9]
	v_mov_b64_e32 v[54:55], v[6:7]
	v_mov_b64_e32 v[52:53], v[4:5]
	v_mov_b64_e32 v[50:51], v[2:3]
	v_mov_b64_e32 v[48:49], v[0:1]
	v_mov_b64_e32 v[44:45], v[12:13]
	v_mov_b64_e32 v[42:43], v[10:11]
	v_mov_b64_e32 v[40:41], v[8:9]
	v_mov_b64_e32 v[38:39], v[6:7]
	v_mov_b64_e32 v[36:37], v[4:5]
	v_mov_b64_e32 v[34:35], v[2:3]
	v_mov_b64_e32 v[32:33], v[0:1]
	v_mov_b64_e32 v[28:29], v[12:13]
	v_mov_b64_e32 v[26:27], v[10:11]
	v_mov_b64_e32 v[24:25], v[8:9]
	v_mov_b64_e32 v[22:23], v[6:7]
	v_mov_b64_e32 v[20:21], v[4:5]
	v_mov_b64_e32 v[18:19], v[2:3]
	v_mov_b64_e32 v[16:17], v[0:1]
	s_mov_b32 s86, 0
	s_cmp_eq_u32 s22, 0x7e0000
	s_mov_b64 s[4:5], -1
	s_cbranch_scc0 .LBB0_519

.LBB0_513:
	s_lshl_b32 s4, s76, 14
	v_add3_u32 v236, s4, v221, v220
	ds_read_b128 v[192:195], v236
	ds_read_b128 v[196:199], v236 offset:8192
	v_add3_u32 v236, s4, v222, v220
	ds_read_b128 v[200:203], v236
	ds_read_b128 v[204:207], v236 offset:8192
	v_add3_u32 v236, s4, v223, v220
	ds_read_b128 v[240:243], v236
	ds_read_b128 v[244:247], v236 offset:8192
	v_add3_u32 v236, s4, v224, v220
	ds_read_b128 v[248:251], v236
	ds_read_b128 v[252:255], v236 offset:8192
	s_waitcnt lgkmcnt(7)
	v_mfma_f32_32x32x16_bf16 v[144:159], v[192:195], v[160:163], 0
	s_waitcnt lgkmcnt(6)
	v_mfma_f32_32x32x16_bf16 v[128:143], v[196:199], v[160:163], 0
	v_add3_u32 v236, s4, v225, v220
	ds_read_b128 v[192:195], v236
	ds_read_b128 v[196:199], v236 offset:8192
	s_waitcnt lgkmcnt(7)
	v_mfma_f32_32x32x16_bf16 v[144:159], v[200:203], v[164:167], v[144:159]
	s_waitcnt lgkmcnt(6)
	v_mfma_f32_32x32x16_bf16 v[128:143], v[204:207], v[164:167], v[128:143]
	v_add3_u32 v236, s4, v227, v220
	ds_read_b128 v[200:203], v236
	ds_read_b128 v[204:207], v236 offset:8192
	s_waitcnt lgkmcnt(7)
	v_mfma_f32_32x32x16_bf16 v[144:159], v[240:243], v[168:171], v[144:159]
	s_waitcnt lgkmcnt(6)
	v_mfma_f32_32x32x16_bf16 v[128:143], v[244:247], v[168:171], v[128:143]
	v_add3_u32 v236, s4, v228, v220
	ds_read_b128 v[240:243], v236
	ds_read_b128 v[244:247], v236 offset:8192
	s_waitcnt lgkmcnt(7)
	v_mfma_f32_32x32x16_bf16 v[144:159], v[248:251], v[172:175], v[144:159]
	s_waitcnt lgkmcnt(6)
	v_mfma_f32_32x32x16_bf16 v[128:143], v[252:255], v[172:175], v[128:143]
	v_add3_u32 v236, s4, v229, v220
	ds_read_b128 v[248:251], v236
	ds_read_b128 v[252:255], v236 offset:8192
	s_waitcnt lgkmcnt(7)
	v_mfma_f32_32x32x16_bf16 v[144:159], v[192:195], v[176:179], v[144:159]
	s_waitcnt lgkmcnt(6)
	v_mfma_f32_32x32x16_bf16 v[128:143], v[196:199], v[176:179], v[128:143]
	s_waitcnt lgkmcnt(5)
	v_mfma_f32_32x32x16_bf16 v[144:159], v[200:203], v[180:183], v[144:159]
	s_waitcnt lgkmcnt(4)
	v_mfma_f32_32x32x16_bf16 v[128:143], v[204:207], v[180:183], v[128:143]
	s_waitcnt lgkmcnt(3)
	v_mfma_f32_32x32x16_bf16 v[144:159], v[240:243], v[184:187], v[144:159]
	s_waitcnt lgkmcnt(2)
	v_mfma_f32_32x32x16_bf16 v[128:143], v[244:247], v[184:187], v[128:143]
	s_waitcnt lgkmcnt(1)
	v_mfma_f32_32x32x16_bf16 v[144:159], v[248:251], v[188:191], v[144:159]
	s_waitcnt lgkmcnt(0)
	v_mfma_f32_32x32x16_bf16 v[128:143], v[252:255], v[188:191], v[128:143]
	s_nop 9
	v_max_f32_e32 v192, v144, v145
	v_max3_f32 v192, v192, v146, v147
	v_max3_f32 v192, v192, v148, v149
	v_max3_f32 v192, v192, v150, v151
	v_max3_f32 v192, v192, v152, v153
	v_max3_f32 v192, v192, v154, v155
	v_max3_f32 v192, v192, v156, v157
	v_max3_f32 v192, v192, v158, v159
	v_max3_f32 v192, v192, v128, v129
	v_max3_f32 v192, v192, v130, v131
	v_max3_f32 v192, v192, v132, v133
	v_max3_f32 v192, v192, v134, v135
	v_max3_f32 v192, v192, v136, v137
	v_max3_f32 v192, v192, v138, v139
	v_max3_f32 v192, v192, v140, v141
	v_max3_f32 v192, v192, v142, v143
	v_mov_b32_e32 v193, v192
	s_nop 1
	v_permlane32_swap_b32_e32 v192, v193
	v_max_f32_e32 v192, v192, v193
	v_sub_f32_e32 v193, v192, v231
	v_cmp_ge_f32_e32 vcc, s38, v193
	v_max_f32_e32 v234, v231, v192
	v_sub_f32_e32 v192, v231, v234
	v_mul_f32_e32 v192, 0x3e0293ee, v192
	v_exp_f32_e32 v192, v192
	s_cmp_eq_u64 vcc, exec
	s_cselect_b64 s[4:5], -1, 0
	v_cndmask_b32_e64 v233, v192, 1.0, s[4:5]
	v_cmp_gt_f32_e32 vcc, 1.0, v233
	s_cbranch_vccz .LBB0_517
	s_and_saveexec_b64 s[24:25], s[0:1]
	ds_write_b32 v226, v233 offset:128
	s_or_b64 exec, exec, s[24:25]
	s_waitcnt lgkmcnt(0)
	v_add_u32_e32 v192, s21, v210
	ds_read_b128 v[204:207], v192 offset:224
	ds_read_b128 v[200:203], v192 offset:192
	ds_read_b128 v[196:199], v192 offset:160
	ds_read_b128 v[192:195], v192 offset:128
	s_waitcnt lgkmcnt(3)
	v_pk_mul_f32 v[12:13], v[12:13], v[204:205]
	s_waitcnt lgkmcnt(2)
	v_pk_mul_f32 v[8:9], v[8:9], v[200:201]
	s_waitcnt lgkmcnt(1)
	v_pk_mul_f32 v[4:5], v[4:5], v[196:197]
	v_pk_mul_f32 v[14:15], v[14:15], v[206:207]
	v_pk_mul_f32 v[10:11], v[10:11], v[202:203]
	v_pk_mul_f32 v[6:7], v[6:7], v[198:199]
	s_waitcnt lgkmcnt(0)
	v_pk_mul_f32 v[2:3], v[2:3], v[194:195]
	v_pk_mul_f32 v[0:1], v[0:1], v[192:193]
	v_pk_mul_f32 v[124:125], v[124:125], v[204:205]
	v_pk_mul_f32 v[120:121], v[120:121], v[200:201]
	v_pk_mul_f32 v[116:117], v[116:117], v[196:197]
	v_pk_mul_f32 v[126:127], v[126:127], v[206:207]
	v_pk_mul_f32 v[122:123], v[122:123], v[202:203]
	v_pk_mul_f32 v[118:119], v[118:119], v[198:199]
	v_pk_mul_f32 v[114:115], v[114:115], v[194:195]
	v_pk_mul_f32 v[112:113], v[112:113], v[192:193]
	v_pk_mul_f32 v[108:109], v[108:109], v[204:205]
	v_pk_mul_f32 v[104:105], v[104:105], v[200:201]
	v_pk_mul_f32 v[100:101], v[100:101], v[196:197]
	v_pk_mul_f32 v[110:111], v[110:111], v[206:207]
	v_pk_mul_f32 v[106:107], v[106:107], v[202:203]
	v_pk_mul_f32 v[102:103], v[102:103], v[198:199]
	v_pk_mul_f32 v[98:99], v[98:99], v[194:195]
	v_pk_mul_f32 v[96:97], v[96:97], v[192:193]
	v_pk_mul_f32 v[92:93], v[92:93], v[204:205]
	v_pk_mul_f32 v[88:89], v[88:89], v[200:201]
	v_pk_mul_f32 v[84:85], v[84:85], v[196:197]
	v_pk_mul_f32 v[94:95], v[94:95], v[206:207]
	v_pk_mul_f32 v[90:91], v[90:91], v[202:203]
	v_pk_mul_f32 v[86:87], v[86:87], v[198:199]
	v_pk_mul_f32 v[82:83], v[82:83], v[194:195]
	v_pk_mul_f32 v[80:81], v[80:81], v[192:193]
	v_pk_mul_f32 v[76:77], v[76:77], v[204:205]
	v_pk_mul_f32 v[72:73], v[72:73], v[200:201]
	v_pk_mul_f32 v[68:69], v[68:69], v[196:197]
	v_pk_mul_f32 v[78:79], v[78:79], v[206:207]
	v_pk_mul_f32 v[74:75], v[74:75], v[202:203]
	v_pk_mul_f32 v[70:71], v[70:71], v[198:199]
	v_pk_mul_f32 v[66:67], v[66:67], v[194:195]
	v_pk_mul_f32 v[64:65], v[64:65], v[192:193]
	v_pk_mul_f32 v[60:61], v[60:61], v[204:205]
	v_pk_mul_f32 v[56:57], v[56:57], v[200:201]
	v_pk_mul_f32 v[52:53], v[52:53], v[196:197]
	v_pk_mul_f32 v[62:63], v[62:63], v[206:207]
	v_pk_mul_f32 v[58:59], v[58:59], v[202:203]
	v_pk_mul_f32 v[54:55], v[54:55], v[198:199]
	v_pk_mul_f32 v[50:51], v[50:51], v[194:195]
	v_pk_mul_f32 v[48:49], v[48:49], v[192:193]
	v_pk_mul_f32 v[44:45], v[44:45], v[204:205]
	v_pk_mul_f32 v[40:41], v[40:41], v[200:201]
	v_pk_mul_f32 v[36:37], v[36:37], v[196:197]
	v_pk_mul_f32 v[46:47], v[46:47], v[206:207]
	v_pk_mul_f32 v[42:43], v[42:43], v[202:203]
	v_pk_mul_f32 v[38:39], v[38:39], v[198:199]
	v_pk_mul_f32 v[34:35], v[34:35], v[194:195]
	v_pk_mul_f32 v[32:33], v[32:33], v[192:193]
	v_pk_mul_f32 v[28:29], v[28:29], v[204:205]
	v_pk_mul_f32 v[24:25], v[24:25], v[200:201]
	v_pk_mul_f32 v[20:21], v[20:21], v[196:197]
	v_pk_mul_f32 v[30:31], v[30:31], v[206:207]
	v_pk_mul_f32 v[26:27], v[26:27], v[202:203]
	v_pk_mul_f32 v[22:23], v[22:23], v[198:199]
	v_pk_mul_f32 v[18:19], v[18:19], v[194:195]
	v_pk_mul_f32 v[16:17], v[16:17], v[192:193]

.LBB0_902:
	s_xor_b64 s[18:19], s[4:5], -1
	s_lshl_b64 s[4:5], s[0:1], 1
	s_add_u32 s22, s62, s4
	s_addc_u32 s23, s63, s5
	v_mov_b32_e32 v2, v208
	s_add_u32 s0, s64, s4
	s_addc_u32 s1, s65, s5
	v_readfirstlane_b32 s20, v2
	s_ashr_i32 s24, s20, 6
	s_and_b32 s20, s20, 0x3fffffc0
	s_lshl_b32 s20, s20, 2
	v_and_b32_e32 v219, 31, v2
	s_add_i32 s21, s20, 0
	s_lshl_b32 s20, s24, 5
	v_or_b32_e32 v0, s20, v219
	s_waitcnt lgkmcnt(0)
	v_ashrrev_i32_e32 v1, 31, v0
	v_bfe_u32 v218, v2, 5, 1
	v_lshlrev_b64 v[0:1], 11, v[0:1]
	v_lshl_add_u64 v[0:1], s[22:23], 0, v[0:1]
	v_lshlrev_b32_e32 v210, 4, v218
	v_lshl_add_u64 v[0:1], v[0:1], 0, v[210:211]
	global_load_dwordx4 v[160:163], v[0:1], off
	global_load_dwordx4 v[164:167], v[0:1], off offset:32
	global_load_dwordx4 v[168:171], v[0:1], off offset:64
	global_load_dwordx4 v[172:175], v[0:1], off offset:96
	global_load_dwordx4 v[176:179], v[0:1], off offset:128
	global_load_dwordx4 v[180:183], v[0:1], off offset:160
	global_load_dwordx4 v[184:187], v[0:1], off offset:192
	global_load_dwordx4 v[188:191], v[0:1], off offset:224
	s_lshl_b32 s22, s24, 3
	v_bfe_u32 v1, v2, 4, 2
	v_or_b32_e32 v0, s22, v1
	v_bitop3_b32 v4, v1, v2, 15 bitop3:0x78
	v_ashrrev_i32_e32 v1, 31, v0
	v_lshlrev_b64 v[212:213], 10, v[0:1]
	v_or_b32_e32 v0, 4, v0
	v_and_b32_e32 v3, 15, v2
	v_ashrrev_i32_e32 v1, 31, v0
	v_bitop3_b32 v3, v0, v3, 7 bitop3:0x6c
	s_and_b32 s25, s24, 1
	s_lshl_b32 s25, s25, 3
	v_xor_b32_e32 v4, s25, v4
	v_xor_b32_e32 v3, s25, v3
	v_lshlrev_b64 v[214:215], 10, v[0:1]
	v_bfe_u32 v0, v2, 2, 3
	v_bitop3_b32 v0, s22, -13, v0 bitop3:0xc8
	v_lshrrev_b32_e32 v1, 2, v2
	s_lshl_b32 s22, s24, 3
	v_and_b32_e32 v1, 4, v1
	s_and_b32 s22, s22, 8
	v_or3_b32 v0, v0, v1, s22
	s_add_i32 s21, s21, 0x24000
	v_ashrrev_i32_e32 v1, 31, v0
	v_lshlrev_b32_e32 v11, 3, v2
	s_lshl_b32 s22, s24, 11
	v_lshl_or_b32 v212, v4, 3, v212
	v_lshlrev_b64 v[216:217], 10, v[0:1]
	v_and_b32_e32 v0, 32, v2
	v_and_b32_e32 v1, 24, v11
	s_cmp_lg_u32 0, -1
	v_or3_b32 v216, v216, v1, v0
	v_lshlrev_b64 v[0:1], 1, v[212:213]
	s_cselect_b32 s23, 0, 0
	v_and_b32_e32 v10, 63, v2
	v_lshl_or_b32 v214, v3, 3, v214
	v_lshlrev_b32_e32 v12, 4, v2
	v_lshlrev_b32_e32 v13, 1, v2
	v_lshl_add_u64 v[2:3], s[0:1], 0, v[0:1]
	s_add_i32 s79, s22, s23
	s_mov_b32 s25, m0
	s_mov_b32 m0, s79
	s_nop 0
	global_load_lds_dwordx4 v[2:3], off
	s_mov_b32 m0, s25
	v_lshlrev_b64 v[2:3], 1, v[214:215]
	s_or_b32 s25, s22, 0x400
	v_lshl_add_u64 v[4:5], s[0:1], 0, v[2:3]
	s_add_i32 s81, s25, s23
	s_mov_b32 s84, m0
	s_mov_b32 m0, s81
	s_nop 0
	global_load_lds_dwordx4 v[4:5], off
	s_mov_b32 m0, s84
	s_lshl_b32 s24, s24, 12
	v_lshlrev_b64 v[4:5], 1, v[216:217]
	s_add_i32 s84, s23, 0xc000
	v_lshl_add_u64 v[6:7], s[14:15], 0, v[4:5]
	s_add_i32 s81, s24, s84
	s_mov_b32 s85, m0
	s_mov_b32 m0, s81
	s_nop 0
	global_load_lds_dwordx4 v[6:7], off
	s_mov_b32 m0, s85
	s_or_b32 s85, s24, 0x400
	s_add_i32 s86, s85, s84
	v_lshl_add_u64 v[8:9], v[6:7], 0, s[8:9]
	s_mov_b32 s87, m0
	s_mov_b32 m0, s86
	s_nop 0
	global_load_lds_dwordx4 v[8:9], off
	s_mov_b32 m0, s87
	s_or_b32 s86, s24, 0x800
	s_add_i32 s87, s86, s84
	v_lshl_add_u64 v[8:9], v[6:7], 0, s[10:11]
	s_mov_b32 s96, m0
	s_mov_b32 m0, s87
	s_nop 0
	global_load_lds_dwordx4 v[8:9], off
	s_mov_b32 m0, s96
	s_or_b32 s87, s24, 0xc00
	s_add_i32 s96, s87, s84
	s_add_u32 s0, s0, 0x20000
	v_lshl_add_u64 v[6:7], v[6:7], 0, s[12:13]
	s_mov_b32 s97, m0
	s_mov_b32 m0, s96
	s_nop 0
	global_load_lds_dwordx4 v[6:7], off
	s_mov_b32 m0, s97
	s_addc_u32 s1, s1, 0
	s_add_i32 s96, s23, 0x4000
	v_lshl_add_u64 v[0:1], s[0:1], 0, v[0:1]
	s_add_i32 s22, s22, s96
	s_mov_b32 s97, m0
	s_mov_b32 m0, s22
	s_nop 0
	global_load_lds_dwordx4 v[0:1], off
	s_mov_b32 m0, s97
	v_lshl_add_u64 v[0:1], s[0:1], 0, v[2:3]
	s_add_i32 s25, s25, s96
	s_mov_b32 s0, m0
	s_mov_b32 m0, s25
	s_nop 0
	global_load_lds_dwordx4 v[0:1], off
	s_mov_b32 m0, s0
	s_add_i32 s23, s23, 0x14000
	v_lshl_add_u64 v[0:1], s[16:17], 0, v[4:5]
	s_add_i32 s24, s24, s23
	s_mov_b32 s0, m0
	s_mov_b32 m0, s24
	s_nop 0
	global_load_lds_dwordx4 v[0:1], off
	s_mov_b32 m0, s0
	v_lshl_add_u64 v[2:3], v[0:1], 0, s[8:9]
	s_add_i32 s85, s85, s23
	s_mov_b32 s0, m0
	s_mov_b32 m0, s85
	s_nop 0
	global_load_lds_dwordx4 v[2:3], off
	s_mov_b32 m0, s0
	v_lshl_add_u64 v[2:3], v[0:1], 0, s[10:11]
	s_add_i32 s86, s86, s23
	s_mov_b32 s0, m0
	s_mov_b32 m0, s86
	s_nop 0
	global_load_lds_dwordx4 v[2:3], off
	s_mov_b32 m0, s0
	v_lshl_add_u64 v[0:1], v[0:1], 0, s[12:13]
	s_add_i32 s87, s87, s23
	s_mov_b32 s0, m0
	s_mov_b32 m0, s87
	s_nop 0
	global_load_lds_dwordx4 v[0:1], off
	s_mov_b32 m0, s0
	v_and_b32_e32 v0, 0x118, v11
	v_and_b32_e32 v14, 0xc0, v12
	s_movk_i32 s0, 0x70
	v_and_or_b32 v0, v13, 32, v0
	v_and_b32_e32 v1, 0x70, v12
	v_bitop3_b32 v221, v210, v12, s0 bitop3:0x78
	s_movk_i32 s0, 0xc0
	v_add3_u32 v230, v14, s84, v0
	v_mov_b32_e32 v14, v211
	v_mov_b32_e32 v15, v211
	v_bitop3_b32 v222, v210, v1, 32 bitop3:0x36
	v_bitop3_b32 v223, v210, v1, 64 bitop3:0x36
	v_bitop3_b32 v225, v210, v1, s38 bitop3:0x36
	v_bitop3_b32 v226, v210, v1, s39 bitop3:0x36
	v_bitop3_b32 v227, v210, v1, s40 bitop3:0x36
	v_bitop3_b32 v228, v210, v1, s0 bitop3:0x36
	v_bitop3_b32 v229, v210, v1, s41 bitop3:0x36
	v_and_b32_e32 v236, 0x80, v12
	v_xor_b32_e32 v221, v236, v221
	v_xor_b32_e32 v222, v236, v222
	v_xor_b32_e32 v223, v236, v223
	v_xor_b32_e32 v225, v236, v225
	v_xor_b32_e32 v226, v236, v226
	v_xor_b32_e32 v227, v236, v227
	v_xor_b32_e32 v228, v236, v228
	v_xor_b32_e32 v229, v236, v229
	v_cmp_gt_u32_e64 s[0:1], 32, v10
	s_add_u32 s84, s74, s4
	v_mov_b32_e32 v0, v211
	v_mov_b32_e32 v1, v211
	v_mov_b32_e32 v2, v211
	v_mov_b32_e32 v3, v211
	v_mov_b32_e32 v4, v211
	v_mov_b32_e32 v5, v211
	v_mov_b32_e32 v6, v211
	v_mov_b32_e32 v7, v211
	v_mov_b32_e32 v8, v211
	v_mov_b32_e32 v9, v211
	v_mov_b32_e32 v10, v211
	v_mov_b32_e32 v11, v211
	v_mov_b32_e32 v12, v211
	v_mov_b32_e32 v13, v211
	v_mov_b64_e32 v[126:127], v[14:15]
	v_mov_b64_e32 v[110:111], v[14:15]
	v_mov_b64_e32 v[94:95], v[14:15]
	v_mov_b64_e32 v[78:79], v[14:15]
	v_mov_b64_e32 v[62:63], v[14:15]
	v_mov_b64_e32 v[46:47], v[14:15]
	v_mov_b64_e32 v[30:31], v[14:15]
	s_mov_b32 s78, 2
	s_mov_b32 s80, 0
	v_lshlrev_b32_e32 v220, 8, v219
	v_lshl_add_u32 v224, v219, 2, s21
	s_addc_u32 s85, s75, s5
	v_mov_b32_e32 v232, 0
	v_mov_b32_e32 v231, 0xf149f2ca
	s_mov_b64 s[22:23], 0
	v_mov_b64_e32 v[124:125], v[12:13]
	v_mov_b64_e32 v[122:123], v[10:11]
	v_mov_b64_e32 v[120:121], v[8:9]
	v_mov_b64_e32 v[118:119], v[6:7]
	v_mov_b64_e32 v[116:117], v[4:5]
	v_mov_b64_e32 v[114:115], v[2:3]
	v_mov_b64_e32 v[112:113], v[0:1]
	v_mov_b64_e32 v[108:109], v[12:13]
	v_mov_b64_e32 v[106:107], v[10:11]
	v_mov_b64_e32 v[104:105], v[8:9]
	v_mov_b64_e32 v[102:103], v[6:7]
	v_mov_b64_e32 v[100:101], v[4:5]
	v_mov_b64_e32 v[98:99], v[2:3]
	v_mov_b64_e32 v[96:97], v[0:1]
	v_mov_b64_e32 v[92:93], v[12:13]
	v_mov_b64_e32 v[90:91], v[10:11]
	v_mov_b64_e32 v[88:89], v[8:9]
	v_mov_b64_e32 v[86:87], v[6:7]
	v_mov_b64_e32 v[84:85], v[4:5]
	v_mov_b64_e32 v[82:83], v[2:3]
	v_mov_b64_e32 v[80:81], v[0:1]
	v_mov_b64_e32 v[76:77], v[12:13]
	v_mov_b64_e32 v[74:75], v[10:11]
	v_mov_b64_e32 v[72:73], v[8:9]
	v_mov_b64_e32 v[70:71], v[6:7]
	v_mov_b64_e32 v[68:69], v[4:5]
	v_mov_b64_e32 v[66:67], v[2:3]
	v_mov_b64_e32 v[64:65], v[0:1]
	v_mov_b64_e32 v[60:61], v[12:13]
	v_mov_b64_e32 v[58:59], v[10:11]
	v_mov_b64_e32 v[56:57], v[8:9]
	v_mov_b64_e32 v[54:55], v[6:7]
	v_mov_b64_e32 v[52:53], v[4:5]
	v_mov_b64_e32 v[50:51], v[2:3]
	v_mov_b64_e32 v[48:49], v[0:1]
	v_mov_b64_e32 v[44:45], v[12:13]
	v_mov_b64_e32 v[42:43], v[10:11]
	v_mov_b64_e32 v[40:41], v[8:9]
	v_mov_b64_e32 v[38:39], v[6:7]
	v_mov_b64_e32 v[36:37], v[4:5]
	v_mov_b64_e32 v[34:35], v[2:3]
	v_mov_b64_e32 v[32:33], v[0:1]
	v_mov_b64_e32 v[28:29], v[12:13]
	v_mov_b64_e32 v[26:27], v[10:11]
	v_mov_b64_e32 v[24:25], v[8:9]
	v_mov_b64_e32 v[22:23], v[6:7]
	v_mov_b64_e32 v[20:21], v[4:5]
	v_mov_b64_e32 v[18:19], v[2:3]
	v_mov_b64_e32 v[16:17], v[0:1]
	s_mov_b32 s86, 0
	s_cmp_eq_u32 s22, 0x7e0000
	s_mov_b64 s[4:5], -1
	s_cbranch_scc0 .LBB0_912

.LBB0_906:
	s_lshl_b32 s4, s80, 14
	v_add3_u32 v236, s4, v221, v220
	ds_read_b128 v[192:195], v236
	ds_read_b128 v[196:199], v236 offset:8192
	v_add3_u32 v236, s4, v222, v220
	ds_read_b128 v[200:203], v236
	ds_read_b128 v[204:207], v236 offset:8192
	v_add3_u32 v236, s4, v223, v220
	ds_read_b128 v[240:243], v236
	ds_read_b128 v[244:247], v236 offset:8192
	v_add3_u32 v236, s4, v225, v220
	ds_read_b128 v[248:251], v236
	ds_read_b128 v[252:255], v236 offset:8192
	s_waitcnt lgkmcnt(7)
	v_mfma_f32_32x32x16_bf16 v[144:159], v[192:195], v[160:163], 0
	s_waitcnt lgkmcnt(6)
	v_mfma_f32_32x32x16_bf16 v[128:143], v[196:199], v[160:163], 0
	v_add3_u32 v236, s4, v226, v220
	ds_read_b128 v[192:195], v236
	ds_read_b128 v[196:199], v236 offset:8192
	s_waitcnt lgkmcnt(7)
	v_mfma_f32_32x32x16_bf16 v[144:159], v[200:203], v[164:167], v[144:159]
	s_waitcnt lgkmcnt(6)
	v_mfma_f32_32x32x16_bf16 v[128:143], v[204:207], v[164:167], v[128:143]
	v_add3_u32 v236, s4, v227, v220
	ds_read_b128 v[200:203], v236
	ds_read_b128 v[204:207], v236 offset:8192
	s_waitcnt lgkmcnt(7)
	v_mfma_f32_32x32x16_bf16 v[144:159], v[240:243], v[168:171], v[144:159]
	s_waitcnt lgkmcnt(6)
	v_mfma_f32_32x32x16_bf16 v[128:143], v[244:247], v[168:171], v[128:143]
	v_add3_u32 v236, s4, v228, v220
	ds_read_b128 v[240:243], v236
	ds_read_b128 v[244:247], v236 offset:8192
	s_waitcnt lgkmcnt(7)
	v_mfma_f32_32x32x16_bf16 v[144:159], v[248:251], v[172:175], v[144:159]
	s_waitcnt lgkmcnt(6)
	v_mfma_f32_32x32x16_bf16 v[128:143], v[252:255], v[172:175], v[128:143]
	v_add3_u32 v236, s4, v229, v220
	ds_read_b128 v[248:251], v236
	ds_read_b128 v[252:255], v236 offset:8192
	s_waitcnt lgkmcnt(7)
	v_mfma_f32_32x32x16_bf16 v[144:159], v[192:195], v[176:179], v[144:159]
	s_waitcnt lgkmcnt(6)
	v_mfma_f32_32x32x16_bf16 v[128:143], v[196:199], v[176:179], v[128:143]
	s_waitcnt lgkmcnt(5)
	v_mfma_f32_32x32x16_bf16 v[144:159], v[200:203], v[180:183], v[144:159]
	s_waitcnt lgkmcnt(4)
	v_mfma_f32_32x32x16_bf16 v[128:143], v[204:207], v[180:183], v[128:143]
	s_waitcnt lgkmcnt(3)
	v_mfma_f32_32x32x16_bf16 v[144:159], v[240:243], v[184:187], v[144:159]
	s_waitcnt lgkmcnt(2)
	v_mfma_f32_32x32x16_bf16 v[128:143], v[244:247], v[184:187], v[128:143]
	s_waitcnt lgkmcnt(1)
	v_mfma_f32_32x32x16_bf16 v[144:159], v[248:251], v[188:191], v[144:159]
	s_waitcnt lgkmcnt(0)
	v_mfma_f32_32x32x16_bf16 v[128:143], v[252:255], v[188:191], v[128:143]
	v_max_f32_e32 v194, v231, v231
	s_nop 9
	v_max_f32_e32 v192, v144, v145
	v_max3_f32 v192, v192, v146, v147
	v_max3_f32 v192, v192, v148, v149
	v_max3_f32 v192, v192, v150, v151
	v_max3_f32 v192, v192, v152, v153
	v_max3_f32 v192, v192, v154, v155
	v_max3_f32 v192, v192, v156, v157
	v_max3_f32 v192, v192, v158, v159
	v_max3_f32 v192, v192, v128, v129
	v_max3_f32 v192, v192, v130, v131
	v_max3_f32 v192, v192, v132, v133
	v_max3_f32 v192, v192, v134, v135
	v_max3_f32 v192, v192, v136, v137
	v_max3_f32 v192, v192, v138, v139
	v_max3_f32 v192, v192, v140, v141
	v_max3_f32 v192, v192, v142, v143
	v_mov_b32_e32 v193, v192
	s_nop 1
	v_permlane32_swap_b32_e32 v192, v193
	v_max_f32_e32 v192, v192, v193
	v_max_f32_e32 v234, v194, v192
	v_sub_f32_e32 v193, v192, v231
	v_sub_f32_e32 v192, v231, v234
	v_mul_f32_e32 v192, 0x3e0293ee, v192
	v_exp_f32_e32 v192, v192
	v_cmp_ge_f32_e32 vcc, s42, v193
	s_cmp_eq_u64 vcc, exec
	s_cselect_b64 s[4:5], -1, 0
	v_cndmask_b32_e64 v233, v192, 1.0, s[4:5]
	v_cmp_gt_f32_e32 vcc, 1.0, v233
	s_cbranch_vccz .LBB0_910
	s_and_saveexec_b64 s[24:25], s[0:1]
	ds_write_b32 v224, v233 offset:128
	s_or_b64 exec, exec, s[24:25]
	s_waitcnt lgkmcnt(0)
	v_add_u32_e32 v192, s21, v210
	ds_read_b128 v[204:207], v192 offset:224
	ds_read_b128 v[200:203], v192 offset:192
	ds_read_b128 v[196:199], v192 offset:160
	ds_read_b128 v[192:195], v192 offset:128
	s_waitcnt lgkmcnt(3)
	v_pk_mul_f32 v[12:13], v[12:13], v[204:205]
	s_waitcnt lgkmcnt(2)
	v_pk_mul_f32 v[8:9], v[8:9], v[200:201]
	s_waitcnt lgkmcnt(1)
	v_pk_mul_f32 v[4:5], v[4:5], v[196:197]
	v_pk_mul_f32 v[14:15], v[14:15], v[206:207]
	v_pk_mul_f32 v[10:11], v[10:11], v[202:203]
	v_pk_mul_f32 v[6:7], v[6:7], v[198:199]
	s_waitcnt lgkmcnt(0)
	v_pk_mul_f32 v[2:3], v[2:3], v[194:195]
	v_pk_mul_f32 v[0:1], v[0:1], v[192:193]
	v_pk_mul_f32 v[124:125], v[124:125], v[204:205]
	v_pk_mul_f32 v[120:121], v[120:121], v[200:201]
	v_pk_mul_f32 v[116:117], v[116:117], v[196:197]
	v_pk_mul_f32 v[126:127], v[126:127], v[206:207]
	v_pk_mul_f32 v[122:123], v[122:123], v[202:203]
	v_pk_mul_f32 v[118:119], v[118:119], v[198:199]
	v_pk_mul_f32 v[114:115], v[114:115], v[194:195]
	v_pk_mul_f32 v[112:113], v[112:113], v[192:193]
	v_pk_mul_f32 v[108:109], v[108:109], v[204:205]
	v_pk_mul_f32 v[104:105], v[104:105], v[200:201]
	v_pk_mul_f32 v[100:101], v[100:101], v[196:197]
	v_pk_mul_f32 v[110:111], v[110:111], v[206:207]
	v_pk_mul_f32 v[106:107], v[106:107], v[202:203]
	v_pk_mul_f32 v[102:103], v[102:103], v[198:199]
	v_pk_mul_f32 v[98:99], v[98:99], v[194:195]
	v_pk_mul_f32 v[96:97], v[96:97], v[192:193]
	v_pk_mul_f32 v[92:93], v[92:93], v[204:205]
	v_pk_mul_f32 v[88:89], v[88:89], v[200:201]
	v_pk_mul_f32 v[84:85], v[84:85], v[196:197]
	v_pk_mul_f32 v[94:95], v[94:95], v[206:207]
	v_pk_mul_f32 v[90:91], v[90:91], v[202:203]
	v_pk_mul_f32 v[86:87], v[86:87], v[198:199]
	v_pk_mul_f32 v[82:83], v[82:83], v[194:195]
	v_pk_mul_f32 v[80:81], v[80:81], v[192:193]
	v_pk_mul_f32 v[76:77], v[76:77], v[204:205]
	v_pk_mul_f32 v[72:73], v[72:73], v[200:201]
	v_pk_mul_f32 v[68:69], v[68:69], v[196:197]
	v_pk_mul_f32 v[78:79], v[78:79], v[206:207]
	v_pk_mul_f32 v[74:75], v[74:75], v[202:203]
	v_pk_mul_f32 v[70:71], v[70:71], v[198:199]
	v_pk_mul_f32 v[66:67], v[66:67], v[194:195]
	v_pk_mul_f32 v[64:65], v[64:65], v[192:193]
	v_pk_mul_f32 v[60:61], v[60:61], v[204:205]
	v_pk_mul_f32 v[56:57], v[56:57], v[200:201]
	v_pk_mul_f32 v[52:53], v[52:53], v[196:197]
	v_pk_mul_f32 v[62:63], v[62:63], v[206:207]
	v_pk_mul_f32 v[58:59], v[58:59], v[202:203]
	v_pk_mul_f32 v[54:55], v[54:55], v[198:199]
	v_pk_mul_f32 v[50:51], v[50:51], v[194:195]
	v_pk_mul_f32 v[48:49], v[48:49], v[192:193]
	v_pk_mul_f32 v[44:45], v[44:45], v[204:205]
	v_pk_mul_f32 v[40:41], v[40:41], v[200:201]
	v_pk_mul_f32 v[36:37], v[36:37], v[196:197]
	v_pk_mul_f32 v[46:47], v[46:47], v[206:207]
	v_pk_mul_f32 v[42:43], v[42:43], v[202:203]
	v_pk_mul_f32 v[38:39], v[38:39], v[198:199]
	v_pk_mul_f32 v[34:35], v[34:35], v[194:195]
	v_pk_mul_f32 v[32:33], v[32:33], v[192:193]
	v_pk_mul_f32 v[28:29], v[28:29], v[204:205]
	v_pk_mul_f32 v[24:25], v[24:25], v[200:201]
	v_pk_mul_f32 v[20:21], v[20:21], v[196:197]
	v_pk_mul_f32 v[30:31], v[30:31], v[206:207]
	v_pk_mul_f32 v[26:27], v[26:27], v[202:203]
	v_pk_mul_f32 v[22:23], v[22:23], v[198:199]
	v_pk_mul_f32 v[18:19], v[18:19], v[194:195]
	v_pk_mul_f32 v[16:17], v[16:17], v[192:193]
